# phase-0 weight conversion offload to idle half-rounds, ranges 14528/17328/20328
# baseline (speedup 1.0000x reference)
.LBB0_20:
	s_lshr_b32 s89, s77, 6
	s_load_dwordx16 s[8:23], s[0:1], 0x40
	s_cmp_lt_i32 s28, 1
	s_cselect_b64 s[0:1], -1, 0
	s_cmp_gt_i32 s29, 0
	s_cselect_b64 s[2:3], -1, 0
	s_and_b64 s[2:3], s[0:1], s[2:3]
	s_andn2_b64 vcc, exec, s[2:3]
	v_and_b32_e32 v227, 63, v226
	s_cbranch_vccnz .LBB0_42
	s_mov_b32 s96, 0
	s_mov_b32 s97, 0x38c0
	s_lshl_b32 s0, s76, 3
	s_add_i32 s4, s0, s89

.Lp0call_1:
	v_writelane_b32 v251, s0, 0
	v_writelane_b32 v251, s1, 1
	v_writelane_b32 v251, s4, 2
	v_writelane_b32 v251, s5, 3
	v_writelane_b32 v251, s26, 4
	v_writelane_b32 v251, s27, 5
	v_writelane_b32 v251, s30, 6
	v_writelane_b32 v251, s31, 7
	v_writelane_b32 v251, s34, 8
	v_writelane_b32 v251, s35, 9
	v_writelane_b32 v251, s52, 10
	v_writelane_b32 v251, s53, 11
	v_writelane_b32 v251, s54, 12
	v_writelane_b32 v251, s55, 13
	v_writelane_b32 v251, s56, 14
	v_writelane_b32 v251, s57, 15
	v_writelane_b32 v251, s58, 16
	v_writelane_b32 v251, s59, 17
	v_writelane_b32 v251, s60, 18
	v_writelane_b32 v251, s61, 19
	v_writelane_b32 v251, s62, 20
	v_writelane_b32 v251, s63, 21
	v_writelane_b32 v251, s64, 22
	v_writelane_b32 v251, s65, 23
	v_writelane_b32 v251, s66, 24
	v_writelane_b32 v251, s67, 25
	v_writelane_b32 v251, s68, 26
	v_writelane_b32 v251, s69, 27
	v_writelane_b32 v251, s70, 28
	v_writelane_b32 v251, s71, 29
	v_writelane_b32 v251, s33, 30
	v_writelane_b32 v251, s40, 31
	v_writelane_b32 v251, s41, 32
	v_writelane_b32 v251, s42, 33
	v_writelane_b32 v251, s43, 34
	v_writelane_b32 v251, s89, 35
	v_writelane_b32 v251, vcc_lo, 36
	v_writelane_b32 v251, vcc_hi, 37
	s_nop 1
	v_readlane_b32 s0, v250, 0
	v_readlane_b32 s1, v250, 1
	s_nop 3
	s_sub_u32 s0, s0, 0x90
	s_subb_u32 s1, s1, 0
	s_load_dwordx4 s[40:43], s[0:1], 0x10
	s_lshr_b32 s89, s77, 6
	s_sub_i32 s4, s6, 0x80
	s_lshl_b32 s4, s4, 3
	s_add_i32 s4, s4, s89
	s_add_i32 s4, s4, 0x38c0
	s_mov_b32 s33, 0x80
	s_mov_b32 s97, 0x43b0
	s_mov_b32 s96, 1
	s_waitcnt vmcnt(0) lgkmcnt(0)
	s_branch .Lp0_entry

.Lp0call_2:
	v_writelane_b32 v251, s0, 0
	v_writelane_b32 v251, s1, 1
	v_writelane_b32 v251, s4, 2
	v_writelane_b32 v251, s5, 3
	v_writelane_b32 v251, s26, 4
	v_writelane_b32 v251, s27, 5
	v_writelane_b32 v251, s30, 6
	v_writelane_b32 v251, s31, 7
	v_writelane_b32 v251, s34, 8
	v_writelane_b32 v251, s35, 9
	v_writelane_b32 v251, s52, 10
	v_writelane_b32 v251, s53, 11
	v_writelane_b32 v251, s54, 12
	v_writelane_b32 v251, s55, 13
	v_writelane_b32 v251, s56, 14
	v_writelane_b32 v251, s57, 15
	v_writelane_b32 v251, s58, 16
	v_writelane_b32 v251, s59, 17
	v_writelane_b32 v251, s60, 18
	v_writelane_b32 v251, s61, 19
	v_writelane_b32 v251, s62, 20
	v_writelane_b32 v251, s63, 21
	v_writelane_b32 v251, s64, 22
	v_writelane_b32 v251, s65, 23
	v_writelane_b32 v251, s66, 24
	v_writelane_b32 v251, s67, 25
	v_writelane_b32 v251, s68, 26
	v_writelane_b32 v251, s69, 27
	v_writelane_b32 v251, s70, 28
	v_writelane_b32 v251, s71, 29
	v_writelane_b32 v251, s33, 30
	v_writelane_b32 v251, s40, 31
	v_writelane_b32 v251, s41, 32
	v_writelane_b32 v251, s42, 33
	v_writelane_b32 v251, s43, 34
	v_writelane_b32 v251, s89, 35
	v_writelane_b32 v251, vcc_lo, 36
	v_writelane_b32 v251, vcc_hi, 37
	s_nop 1
	v_readlane_b32 s0, v250, 0
	v_readlane_b32 s1, v250, 1
	s_nop 3
	s_sub_u32 s0, s0, 0x90
	s_subb_u32 s1, s1, 0
	s_load_dwordx4 s[40:43], s[0:1], 0x10
	s_lshr_b32 s89, s77, 6
	s_sub_i32 s4, s6, 0x80
	s_lshl_b32 s4, s4, 3
	s_add_i32 s4, s4, s89
	s_add_i32 s4, s4, 0x43b0
	s_mov_b32 s33, 0x80
	s_mov_b32 s97, 0x4f68
	s_mov_b32 s96, 2
	s_waitcnt vmcnt(0) lgkmcnt(0)
	s_branch .Lp0_entry

.Lp0call_3:
	v_writelane_b32 v251, s0, 0
	v_writelane_b32 v251, s1, 1
	v_writelane_b32 v251, s4, 2
	v_writelane_b32 v251, s5, 3
	v_writelane_b32 v251, s26, 4
	v_writelane_b32 v251, s27, 5
	v_writelane_b32 v251, s30, 6
	v_writelane_b32 v251, s31, 7
	v_writelane_b32 v251, s34, 8
	v_writelane_b32 v251, s35, 9
	v_writelane_b32 v251, s52, 10
	v_writelane_b32 v251, s53, 11
	v_writelane_b32 v251, s54, 12
	v_writelane_b32 v251, s55, 13
	v_writelane_b32 v251, s56, 14
	v_writelane_b32 v251, s57, 15
	v_writelane_b32 v251, s58, 16
	v_writelane_b32 v251, s59, 17
	v_writelane_b32 v251, s60, 18
	v_writelane_b32 v251, s61, 19
	v_writelane_b32 v251, s62, 20
	v_writelane_b32 v251, s63, 21
	v_writelane_b32 v251, s64, 22
	v_writelane_b32 v251, s65, 23
	v_writelane_b32 v251, s66, 24
	v_writelane_b32 v251, s67, 25
	v_writelane_b32 v251, s68, 26
	v_writelane_b32 v251, s69, 27
	v_writelane_b32 v251, s70, 28
	v_writelane_b32 v251, s71, 29
	v_writelane_b32 v251, s33, 30
	v_writelane_b32 v251, s40, 31
	v_writelane_b32 v251, s41, 32
	v_writelane_b32 v251, s42, 33
	v_writelane_b32 v251, s43, 34
	v_writelane_b32 v251, s89, 35
	v_writelane_b32 v251, vcc_lo, 36
	v_writelane_b32 v251, vcc_hi, 37
	s_nop 1
	v_readlane_b32 s0, v250, 0
	v_readlane_b32 s1, v250, 1
	s_nop 3
	s_sub_u32 s0, s0, 0x90
	s_subb_u32 s1, s1, 0
	s_load_dwordx4 s[40:43], s[0:1], 0x10
	s_lshr_b32 s89, s77, 6
	s_sub_i32 s4, s6, 0x80
	s_lshl_b32 s4, s4, 3
	s_add_i32 s4, s4, s89
	s_add_i32 s4, s4, 0x4f68
	s_mov_b32 s33, 0x80
	s_mov_b32 s97, 0x5800
	s_mov_b32 s96, 3
	s_waitcnt vmcnt(0) lgkmcnt(0)
	s_branch .Lp0_entry
